# qkprep row loop: next row's loads issued one iteration ahead (register copies in the body); merge epilogue sigmoid computed 3 units ahead
# speedup vs baseline: 1.0206x; 1.0031x over previous
.LBB0_789:
	s_or_b64 exec, exec, s[0:1]
	v_readlane_b32 s0, v255, 26
	v_readlane_b32 s1, v255, 27
	s_xor_b64 s[0:1], s[0:1], -1
	v_writelane_b32 v255, s0, 30
	s_mov_b64 s[4:5], s[76:77]
	s_waitcnt lgkmcnt(0)
	v_writelane_b32 v255, s1, 31
	s_mov_b32 s0, s3
	s_mov_b32 s1, -1
	s_barrier
	s_mov_b32 s12, s96
	v_mbcnt_lo_u32_b32 v0, s1, 0
	v_mbcnt_hi_u32_b32 v0, s1, v0
	v_lshl_add_u32 v0, s0, 6, v0
	v_readlane_b32 s0, v255, 1
	v_ashrrev_i32_e32 v2, 6, v0
	s_nop 0
	v_add_u32_e32 v46, s0, v2
	s_movk_i32 s0, 0x4800
	v_mbcnt_lo_u32_b32 v2, -1, 0
	v_cmp_gt_i32_e32 vcc, s0, v46
	v_mbcnt_hi_u32_b32 v222, -1, v2
	s_and_saveexec_b64 s[0:1], vcc
	s_cbranch_execz .LBB0_806
	s_load_dwordx4 s[8:11], s[4:5], 0x48
	s_load_dwordx2 s[16:17], s[4:5], 0xb8
	s_lshl_b32 s40, s97, 6
	s_lshl_b64 s[6:7], s[40:41], 2
	v_lshlrev_b32_e32 v18, 5, v0
	s_waitcnt lgkmcnt(0)
	s_add_u32 s4, s10, s6
	v_and_b32_e32 v14, 0xe0, v18
	s_addc_u32 s5, s11, s7
	global_load_dwordx4 v[2:5], v14, s[4:5] offset:16
	global_load_dwordx4 v[6:9], v14, s[4:5]
	s_add_u32 s4, s8, s6
	s_addc_u32 s5, s9, s7
	global_load_dwordx4 v[10:13], v14, s[4:5] offset:16
	s_nop 0
	global_load_dwordx4 v[14:17], v14, s[4:5]
	v_and_b32_e32 v20, 63, v0
	v_and_b32_e32 v19, 4, v0
	v_lshlrev_b32_e32 v0, 3, v0
	v_cmp_eq_u32_e64 s[4:5], 0, v19
	v_mov_b32_e32 v19, 0x200
	v_and_b32_e32 v0, 0x78, v0
	v_lshl_or_b32 v19, v20, 3, v19
	v_or_b32_e32 v0, 0x500, v0
	v_cmp_gt_u32_e64 s[6:7], 16, v20
	s_mov_b64 s[10:11], 0x140000
	v_ashrrev_i32_e32 v47, 31, v46
	v_cndmask_b32_e64 v21, v0, v19, s[6:7]
	v_and_b32_e32 v0, 0x60, v18
	v_lshl_add_u64 v[18:19], s[16:17], 0, v[0:1]
	v_lshl_add_u64 v[48:49], v[18:19], 0, s[10:11]
	s_mov_b64 s[10:11], 0x180000
	v_and_b32_e32 v0, 64, v222
	v_lshl_add_u64 v[50:51], v[18:19], 0, s[10:11]
	v_add_u32_e32 v0, 64, v0
	v_xor_b32_e32 v18, 1, v222
	v_cmp_lt_i32_e32 vcc, v18, v0
	s_lshl_b32 s18, s12, 3
	v_lshlrev_b64 v[54:55], 13, v[46:47]
	v_cndmask_b32_e32 v18, v222, v18, vcc
	v_lshlrev_b32_e32 v76, 2, v18
	v_xor_b32_e32 v18, 2, v222
	v_cmp_lt_i32_e32 vcc, v18, v0
	s_ashr_i32 s19, s18, 31
	v_mov_b32_e32 v19, v55
	v_cndmask_b32_e32 v18, v222, v18, vcc
	v_lshlrev_b32_e32 v77, 2, v18
	v_xor_b32_e32 v18, 4, v222
	v_cmp_lt_i32_e32 vcc, v18, v0
	v_cmp_gt_u32_e64 s[8:9], 32, v20
	v_cmp_eq_u32_e64 s[10:11], 0, v20
	v_cndmask_b32_e32 v18, v222, v18, vcc
	v_lshlrev_b32_e32 v78, 2, v18
	v_xor_b32_e32 v18, 8, v222
	v_cmp_lt_i32_e32 vcc, v18, v0
	v_lshlrev_b64 v[52:53], 3, v[46:47]
	s_lshl_b64 s[20:21], s[18:19], 3
	v_cndmask_b32_e32 v18, v222, v18, vcc
	v_lshlrev_b32_e32 v79, 2, v18
	v_xor_b32_e32 v18, 16, v222
	v_cmp_lt_i32_e32 vcc, v18, v0
	s_lshl_b64 s[26:27], s[18:19], 13
	s_mov_b64 s[52:53], 0
	v_cndmask_b32_e32 v18, v222, v18, vcc
	v_lshlrev_b32_e32 v80, 2, v18
	v_xor_b32_e32 v18, 32, v222
	v_cmp_lt_i32_e32 vcc, v18, v0
	s_nop 1
	v_cndmask_b32_e32 v0, v222, v18, vcc
	v_lshl_or_b32 v18, v21, 1, v54
	v_lshlrev_b32_e32 v81, 2, v0
	v_lshl_add_u64 v[56:57], v[18:19], 0, s[94:95]
	v_lshl_or_b32 v54, v20, 4, v54
	v_mov_b32_e32 v126, v46
	v_lshl_add_u64 v[128:129], s[16:17], 0, v[54:55]
	s_mov_b64 s[12:13], 0x2800000
	v_lshl_add_u64 v[88:89], v[128:129], 0, s[12:13]
	global_load_dwordx4 v[90:93], v[88:89], off
	global_load_dwordx4 v[94:97], v[88:89], off offset:1536
	s_mov_b64 s[12:13], 0x2801000
	v_lshl_add_u64 v[88:89], v[128:129], 0, s[12:13]
	global_load_dwordx4 v[102:105], v[88:89], off
	v_lshl_add_u64 v[128:129], s[16:17], 0, v[56:57]
	v_mov_b32_e32 v98, 0
	v_mov_b32_e32 v99, 0
	v_mov_b32_e32 v100, 0
	v_mov_b32_e32 v101, 0
	s_and_saveexec_b64 s[12:13], s[8:9]
	global_load_dwordx4 v[98:101], v[128:129], off
	s_or_b64 exec, exec, s[12:13]
	v_mul_hi_i32 v127, v126, s55
	v_lshrrev_b32_e32 v128, 31, v127
	v_ashrrev_i32_e32 v127, 9, v127
	v_add_u32_e32 v127, v127, v128
	v_mul_i32_i24_e32 v127, 0x900, v127
	v_sub_u32_e32 v127, v126, v127
	v_max_i32_e32 v127, 0x100, v127
	v_lshl_add_u32 v128, v127, 5, v217
	v_mov_b32_e32 v129, 0
	v_lshlrev_b64 v[128:129], 2, v[128:129]
	v_lshl_add_u64 v[88:89], v[48:49], 0, v[128:129]
	v_lshl_add_u64 v[128:129], v[50:51], 0, v[128:129]
	global_load_dwordx4 v[106:109], v[88:89], off
	global_load_dwordx4 v[110:113], v[128:129], off offset:16
	global_load_dwordx4 v[114:117], v[88:89], off offset:16
	global_load_dwordx4 v[118:121], v[128:129], off
	s_waitcnt vmcnt(0)
	s_branch .Lqk_body

.LBB0_792:
	s_waitcnt vmcnt(4)
.Lqk_body:
	v_lshl_add_u64 v[60:61], s[16:17], 0, v[54:55]
	v_add_co_u32_e32 v18, vcc, 0x2800000, v60
	v_mov_b32_e32 v34, 0
	s_nop 0
	v_addc_co_u32_e32 v19, vcc, 0, v61, vcc
	v_mov_b32_e32 v42, v90
	v_mov_b32_e32 v43, v91
	v_mov_b32_e32 v44, v92
	v_mov_b32_e32 v45, v93
	v_mov_b32_e32 v38, v94
	v_mov_b32_e32 v39, v95
	v_mov_b32_e32 v40, v96
	v_mov_b32_e32 v41, v97
	v_lshl_add_u64 v[58:59], s[16:17], 0, v[56:57]
	v_mov_b32_e32 v35, 0
	v_mov_b32_e32 v36, 0
	v_mov_b32_e32 v37, 0
	s_and_saveexec_b64 s[12:13], s[8:9]
	s_cbranch_execz .LBB0_794
	v_mov_b32_e32 v34, v98
	v_mov_b32_e32 v35, v99
	v_mov_b32_e32 v36, v100
	v_mov_b32_e32 v37, v101
.LBB0_794:
	s_or_b64 exec, exec, s[12:13]
	v_add_co_u32_e32 v18, vcc, 0x2801000, v60
	v_mul_hi_i32 v0, v46, s55
	s_nop 0
	v_addc_co_u32_e32 v19, vcc, 0, v61, vcc
	v_mov_b32_e32 v22, v102
	v_mov_b32_e32 v23, v103
	v_mov_b32_e32 v24, v104
	v_mov_b32_e32 v25, v105
	v_lshrrev_b32_e32 v18, 31, v0
	v_ashrrev_i32_e32 v0, 9, v0
	v_add_u32_e32 v0, v0, v18
	v_mul_i32_i24_e32 v0, 0x900, v0
	v_sub_u32_e32 v47, v46, v0
	v_max_i32_e32 v0, 0x100, v47
	v_lshl_add_u32 v0, v0, 5, v217
	v_lshlrev_b64 v[26:27], 2, v[0:1]
	v_lshl_add_u64 v[30:31], v[48:49], 0, v[26:27]
	v_lshl_add_u64 v[32:33], v[50:51], 0, v[26:27]
	v_mov_b32_e32 v18, v106
	v_mov_b32_e32 v19, v107
	v_mov_b32_e32 v20, v108
	v_mov_b32_e32 v21, v109
	s_nop 0
	v_lshlrev_b32_e32 v62, 16, v22
	v_and_b32_e32 v63, 0xffff0000, v22
	v_lshlrev_b32_e32 v64, 16, v23
	v_and_b32_e32 v65, 0xffff0000, v23
	v_lshlrev_b32_e32 v66, 16, v24
	v_and_b32_e32 v67, 0xffff0000, v24
	v_lshlrev_b32_e32 v68, 16, v25
	v_and_b32_e32 v69, 0xffff0000, v25
	v_add_f32_e32 v0, v62, v63
	v_add_f32_e32 v22, v64, v65
	v_add_f32_e32 v23, v66, v67
	v_add_f32_e32 v24, v68, v69
	v_add_f32_e32 v0, v0, v22
	v_add_f32_e32 v22, v23, v24
	v_add_f32_e32 v0, v0, v22
	ds_bpermute_b32 v22, v76, v0
	s_waitcnt lgkmcnt(0)
	v_add_f32_e32 v0, v0, v22
	v_mov_b32_e32 v26, v110
	v_mov_b32_e32 v27, v111
	v_mov_b32_e32 v28, v112
	v_mov_b32_e32 v29, v113
	v_mov_b32_e32 v22, v114
	v_mov_b32_e32 v23, v115
	v_mov_b32_e32 v24, v116
	v_mov_b32_e32 v25, v117
	s_nop 0
	v_mov_b32_e32 v30, v118
	v_mov_b32_e32 v31, v119
	v_mov_b32_e32 v32, v120
	v_mov_b32_e32 v33, v121
	v_add_u32_e32 v126, s18, v46
	s_nop 0
	v_readfirstlane_b32 s12, v126
	s_cmp_gt_i32 s12, 0x47ff
	s_cbranch_scc1 .Lqk_skip_n
	v_lshl_add_u64 v[128:129], v[54:55], 0, s[26:27]
	v_lshl_add_u64 v[128:129], s[16:17], 0, v[128:129]
	s_mov_b64 s[12:13], 0x2800000
	v_lshl_add_u64 v[88:89], v[128:129], 0, s[12:13]
	global_load_dwordx4 v[90:93], v[88:89], off
	global_load_dwordx4 v[94:97], v[88:89], off offset:1536
	s_mov_b64 s[12:13], 0x2801000
	v_lshl_add_u64 v[88:89], v[128:129], 0, s[12:13]
	global_load_dwordx4 v[102:105], v[88:89], off
	v_lshl_add_u64 v[128:129], v[56:57], 0, s[26:27]
	v_lshl_add_u64 v[128:129], s[16:17], 0, v[128:129]
	v_mov_b32_e32 v98, 0
	v_mov_b32_e32 v99, 0
	v_mov_b32_e32 v100, 0
	v_mov_b32_e32 v101, 0
	s_and_saveexec_b64 s[12:13], s[8:9]
	global_load_dwordx4 v[98:101], v[128:129], off
	s_or_b64 exec, exec, s[12:13]
	v_mul_hi_i32 v127, v126, s55
	v_lshrrev_b32_e32 v128, 31, v127
	v_ashrrev_i32_e32 v127, 9, v127
	v_add_u32_e32 v127, v127, v128
	v_mul_i32_i24_e32 v127, 0x900, v127
	v_sub_u32_e32 v127, v126, v127
	v_max_i32_e32 v127, 0x100, v127
	v_lshl_add_u32 v128, v127, 5, v217
	v_mov_b32_e32 v129, 0
	v_lshlrev_b64 v[128:129], 2, v[128:129]
	v_lshl_add_u64 v[88:89], v[48:49], 0, v[128:129]
	v_lshl_add_u64 v[128:129], v[50:51], 0, v[128:129]
	global_load_dwordx4 v[106:109], v[88:89], off
	global_load_dwordx4 v[110:113], v[128:129], off offset:16
	global_load_dwordx4 v[114:117], v[88:89], off offset:16
	global_load_dwordx4 v[118:121], v[128:129], off
.Lqk_skip_n:
	ds_bpermute_b32 v70, v77, v0
	s_waitcnt lgkmcnt(0)
	v_add_f32_e32 v0, v0, v70
	ds_bpermute_b32 v70, v78, v0
	s_waitcnt lgkmcnt(0)
	v_add_f32_e32 v0, v0, v70
	ds_bpermute_b32 v70, v79, v0
	s_waitcnt lgkmcnt(0)
	v_add_f32_e32 v0, v0, v70
	ds_bpermute_b32 v70, v80, v0
	s_waitcnt lgkmcnt(0)
	v_add_f32_e32 v0, v0, v70
	ds_bpermute_b32 v70, v81, v0
	s_waitcnt lgkmcnt(0)
	v_add_f32_e32 v0, v0, v70
	v_fmac_f32_e32 v63, 0xbb000000, v0
	v_fmac_f32_e32 v65, 0xbb000000, v0
	v_fmac_f32_e32 v67, 0xbb000000, v0
	v_fmac_f32_e32 v69, 0xbb000000, v0
	v_fmac_f32_e32 v62, 0xbb000000, v0
	v_fmac_f32_e32 v64, 0xbb000000, v0
	v_fmac_f32_e32 v66, 0xbb000000, v0
	v_fmac_f32_e32 v68, 0xbb000000, v0
	v_mul_f32_e32 v63, v63, v63
	v_mul_f32_e32 v65, v65, v65
	v_mul_f32_e32 v67, v67, v67
	v_mul_f32_e32 v69, v69, v69
	v_fmac_f32_e32 v63, v62, v62
	v_fmac_f32_e32 v65, v64, v64
	v_fmac_f32_e32 v67, v66, v66
	v_fmac_f32_e32 v69, v68, v68
	v_add_f32_e32 v62, v63, v65
	v_add_f32_e32 v63, v67, v69
	v_add_f32_e32 v62, v62, v63
	ds_bpermute_b32 v63, v76, v62
	s_waitcnt lgkmcnt(0)
	v_add_f32_e32 v62, v62, v63
	ds_bpermute_b32 v63, v77, v62
	s_waitcnt lgkmcnt(0)
	v_add_f32_e32 v62, v62, v63
	ds_bpermute_b32 v63, v78, v62
	s_waitcnt lgkmcnt(0)
	v_add_f32_e32 v62, v62, v63
	ds_bpermute_b32 v63, v79, v62
	s_waitcnt lgkmcnt(0)
	v_add_f32_e32 v62, v62, v63
	ds_bpermute_b32 v63, v80, v62
	s_waitcnt lgkmcnt(0)
	v_add_f32_e32 v62, v62, v63
	ds_bpermute_b32 v63, v81, v62
	s_and_saveexec_b64 s[12:13], s[10:11]
	s_cbranch_execz .LBB0_796
	s_waitcnt lgkmcnt(0)
	v_add_f32_e32 v62, v62, v63
	v_fmamk_f32 v62, v62, 0x3b000000, v216
	v_mul_f32_e32 v63, 0x4b800000, v62
	v_cmp_gt_f32_e32 vcc, s33, v62
	v_lshl_add_u64 v[64:65], s[16:17], 0, v[52:53]
	s_nop 0
	v_cndmask_b32_e32 v62, v62, v63, vcc
	v_rsq_f32_e32 v63, v62
	v_mul_f32_e32 v62, 0x3b000000, v0
	v_mul_f32_e32 v0, 0x45800000, v63
	v_cndmask_b32_e32 v63, v63, v0, vcc
	v_add_co_u32_e32 v64, vcc, 0x40000, v64
	s_nop 1
	v_addc_co_u32_e32 v65, vcc, 0, v65, vcc
	global_store_dwordx2 v[64:65], v[62:63], off
.LBB0_796:
	s_or_b64 exec, exec, s[12:13]
	v_lshlrev_b32_e32 v62, 16, v42
	s_waitcnt lgkmcnt(0)
	v_and_b32_e32 v63, 0xffff0000, v42
	v_pk_mul_f32 v[64:65], v[62:63], v[62:63]
	v_lshlrev_b32_e32 v66, 16, v43
	v_and_b32_e32 v67, 0xffff0000, v43
	v_pk_mul_f32 v[42:43], v[66:67], v[66:67]
	v_add_f32_e32 v0, v64, v65
	v_lshlrev_b32_e32 v68, 16, v44
	v_and_b32_e32 v69, 0xffff0000, v44
	v_add_f32_e32 v0, v42, v0
	v_pk_mul_f32 v[70:71], v[68:69], v[68:69]
	v_add_f32_e32 v0, v43, v0
	v_lshlrev_b32_e32 v72, 16, v45
	v_and_b32_e32 v73, 0xffff0000, v45
	v_add_f32_e32 v0, v70, v0
	v_pk_mul_f32 v[44:45], v[72:73], v[72:73]
	v_add_f32_e32 v0, v71, v0
	v_add_f32_e32 v0, v44, v0
	v_add_f32_e32 v0, v45, v0
	ds_bpermute_b32 v42, v76, v0
	v_cmp_lt_i32_e32 vcc, s54, v47
	s_waitcnt lgkmcnt(0)
	v_add_f32_e32 v0, v0, v42
	ds_bpermute_b32 v42, v77, v0
	s_waitcnt lgkmcnt(0)
	v_add_f32_e32 v0, v0, v42
	ds_bpermute_b32 v42, v78, v0
	s_waitcnt lgkmcnt(0)
	v_add_f32_e32 v0, v0, v42
	v_fmamk_f32 v0, v0, 0x3c800000, v216
	v_cmp_gt_f32_e64 s[12:13], s33, v0
	v_mul_f32_e32 v42, 0x4b800000, v0
	s_nop 0
	v_cndmask_b32_e64 v0, v0, v42, s[12:13]
	v_rsq_f32_e32 v0, v0
	s_nop 0
	v_mul_f32_e32 v42, 0x45800000, v0
	v_cndmask_b32_e64 v0, v0, v42, s[12:13]
	v_pk_mul_f32 v[42:43], v[14:15], v[0:1] op_sel_hi:[1,0]
	v_pk_mul_f32 v[44:45], v[16:17], v[0:1] op_sel_hi:[1,0]
	v_pk_mul_f32 v[42:43], v[42:43], v[62:63]
	v_pk_mul_f32 v[62:63], v[10:11], v[0:1] op_sel_hi:[1,0]
	v_pk_mul_f32 v[44:45], v[44:45], v[66:67]
	v_pk_mul_f32 v[64:65], v[62:63], v[68:69]
	v_pk_mul_f32 v[62:63], v[12:13], v[0:1] op_sel_hi:[1,0]
	s_nop 0
	v_pk_mul_f32 v[62:63], v[62:63], v[72:73]
	s_and_saveexec_b64 s[12:13], vcc
	s_cbranch_execz .LBB0_798
	ds_bpermute_b32 v66, v78, v42
	ds_bpermute_b32 v67, v78, v43
	ds_bpermute_b32 v68, v78, v44
	ds_bpermute_b32 v69, v78, v45
	ds_bpermute_b32 v70, v78, v64
	ds_bpermute_b32 v71, v78, v65
	ds_bpermute_b32 v72, v78, v62
	ds_bpermute_b32 v73, v78, v63
	s_waitcnt lgkmcnt(6)
	v_pk_mul_f32 v[66:67], v[30:31], v[66:67]
	s_waitcnt lgkmcnt(4)
	v_pk_mul_f32 v[68:69], v[32:33], v[68:69]
	s_waitcnt lgkmcnt(2)
	v_pk_mul_f32 v[70:71], v[26:27], v[70:71]
	v_cndmask_b32_e64 v67, v67, -v67, s[4:5]
	s_waitcnt lgkmcnt(0)
	v_pk_mul_f32 v[72:73], v[28:29], v[72:73]
	v_cndmask_b32_e64 v66, v66, -v66, s[4:5]
	v_cndmask_b32_e64 v69, v69, -v69, s[4:5]
	v_cndmask_b32_e64 v68, v68, -v68, s[4:5]
	v_cndmask_b32_e64 v71, v71, -v71, s[4:5]
	v_cndmask_b32_e64 v70, v70, -v70, s[4:5]
	v_cndmask_b32_e64 v72, v72, -v72, s[4:5]
	v_cndmask_b32_e64 v73, v73, -v73, s[4:5]
	v_pk_fma_f32 v[62:63], v[24:25], v[62:63], v[72:73]
	v_pk_fma_f32 v[64:65], v[22:23], v[64:65], v[70:71]
	v_pk_fma_f32 v[44:45], v[20:21], v[44:45], v[68:69]
	v_pk_fma_f32 v[42:43], v[18:19], v[42:43], v[66:67]
.LBB0_798:
	s_or_b64 exec, exec, s[12:13]
	v_lshlrev_b32_e32 v66, 16, v38
	v_and_b32_e32 v67, 0xffff0000, v38
	v_lshlrev_b32_e32 v38, 16, v39
	v_and_b32_e32 v39, 0xffff0000, v39
	v_lshlrev_b32_e32 v68, 16, v40
	v_and_b32_e32 v69, 0xffff0000, v40
	v_lshlrev_b32_e32 v40, 16, v41
	v_and_b32_e32 v41, 0xffff0000, v41
	s_and_saveexec_b64 s[12:13], vcc
	s_cbranch_execz .LBB0_800
	ds_bpermute_b32 v70, v78, v66
	ds_bpermute_b32 v71, v78, v67
	s_waitcnt lgkmcnt(0)
	v_pk_mul_f32 v[70:71], v[30:31], v[70:71]
	s_nop 0
	v_cndmask_b32_e64 v71, v71, -v71, s[4:5]
	v_cndmask_b32_e64 v70, v70, -v70, s[4:5]
	v_pk_fma_f32 v[66:67], v[18:19], v[66:67], v[70:71]
	ds_bpermute_b32 v70, v78, v38
	ds_bpermute_b32 v71, v78, v39
	s_waitcnt lgkmcnt(0)
	v_pk_mul_f32 v[70:71], v[32:33], v[70:71]
	s_nop 0
	v_cndmask_b32_e64 v71, v71, -v71, s[4:5]
	v_cndmask_b32_e64 v70, v70, -v70, s[4:5]
	v_pk_fma_f32 v[38:39], v[20:21], v[38:39], v[70:71]
	ds_bpermute_b32 v70, v78, v68
	ds_bpermute_b32 v71, v78, v69
	s_waitcnt lgkmcnt(0)
	v_pk_mul_f32 v[70:71], v[26:27], v[70:71]
	s_nop 0
	v_cndmask_b32_e64 v71, v71, -v71, s[4:5]
	v_cndmask_b32_e64 v70, v70, -v70, s[4:5]
	v_pk_fma_f32 v[68:69], v[22:23], v[68:69], v[70:71]
	ds_bpermute_b32 v70, v78, v40
	ds_bpermute_b32 v71, v78, v41
	s_waitcnt lgkmcnt(0)
	v_pk_mul_f32 v[70:71], v[28:29], v[70:71]
	s_nop 0
	v_cndmask_b32_e64 v71, v71, -v71, s[4:5]
	v_cndmask_b32_e64 v70, v70, -v70, s[4:5]
	v_pk_fma_f32 v[40:41], v[24:25], v[40:41], v[70:71]

.LBB0_802:
	s_or_b64 exec, exec, s[56:57]
	s_and_saveexec_b64 s[12:13], vcc
	s_cbranch_execz .LBB0_804
	ds_bpermute_b32 v36, v78, v70
	ds_bpermute_b32 v37, v78, v71
	s_waitcnt lgkmcnt(0)
	v_pk_mul_f32 v[30:31], v[30:31], v[36:37]
	ds_bpermute_b32 v36, v78, v34
	ds_bpermute_b32 v37, v78, v35
	v_cndmask_b32_e64 v31, v31, -v31, s[4:5]
	v_cndmask_b32_e64 v30, v30, -v30, s[4:5]
	v_pk_fma_f32 v[70:71], v[18:19], v[70:71], v[30:31]
	s_waitcnt lgkmcnt(0)
	v_pk_mul_f32 v[32:33], v[32:33], v[36:37]
	ds_bpermute_b32 v36, v78, v72
	ds_bpermute_b32 v37, v78, v73
	v_cndmask_b32_e64 v33, v33, -v33, s[4:5]
	v_cndmask_b32_e64 v32, v32, -v32, s[4:5]
	v_pk_fma_f32 v[34:35], v[20:21], v[34:35], v[32:33]
	s_waitcnt lgkmcnt(0)
	v_pk_mul_f32 v[26:27], v[26:27], v[36:37]
	ds_bpermute_b32 v36, v78, v74
	ds_bpermute_b32 v37, v78, v75
	v_cndmask_b32_e64 v27, v27, -v27, s[4:5]
	v_cndmask_b32_e64 v26, v26, -v26, s[4:5]
	v_pk_fma_f32 v[72:73], v[22:23], v[72:73], v[26:27]
	s_waitcnt lgkmcnt(0)
	v_pk_mul_f32 v[28:29], v[28:29], v[36:37]
	s_nop 0
	v_cndmask_b32_e64 v28, v28, -v28, s[4:5]
	v_cndmask_b32_e64 v29, v29, -v29, s[4:5]
	v_pk_fma_f32 v[74:75], v[24:25], v[74:75], v[28:29]
.LBB0_804:
	s_or_b64 exec, exec, s[12:13]
	s_nop 0
	v_pk_mul_f32 v[18:19], v[66:67], s[62:63] op_sel_hi:[1,0]
	v_pk_mul_f32 v[20:21], v[38:39], s[62:63] op_sel_hi:[1,0]
	v_cvt_pk_bf16_f32 v18, v18, v19
	v_cvt_pk_bf16_f32 v19, v20, v21
	v_pk_mul_f32 v[20:21], v[68:69], s[62:63] op_sel_hi:[1,0]
	s_nop 0
	v_pk_mul_f32 v[22:23], v[40:41], s[62:63] op_sel_hi:[1,0]
	v_cvt_pk_bf16_f32 v20, v20, v21
	v_cvt_pk_bf16_f32 v21, v22, v23
	v_pk_mul_f32 v[22:23], v[42:43], s[62:63] op_sel_hi:[1,0]
	v_pk_mul_f32 v[24:25], v[44:45], s[62:63] op_sel_hi:[1,0]
	v_cvt_pk_bf16_f32 v22, v22, v23
	v_cvt_pk_bf16_f32 v23, v24, v25
	v_pk_mul_f32 v[24:25], v[64:65], s[62:63] op_sel_hi:[1,0]
	s_nop 0
	v_pk_mul_f32 v[30:31], v[62:63], s[62:63] op_sel_hi:[1,0]
	v_lshl_add_u64 v[26:27], v[60:61], 0, s[94:95]
	s_mov_b64 s[12:13], 0x2800600
	v_cvt_pk_bf16_f32 v24, v24, v25
	v_cvt_pk_bf16_f32 v25, v30, v31
	v_lshl_add_u64 v[28:29], v[60:61], 0, s[12:13]
	global_store_dwordx4 v[26:27], v[22:25], off
	global_store_dwordx4 v[28:29], v[18:21], off
	s_and_saveexec_b64 s[12:13], s[8:9]
	s_cbranch_execz .LBB0_791
	v_cvt_pk_bf16_f32 v18, v70, v71
	v_cvt_pk_bf16_f32 v19, v34, v35
	v_cvt_pk_bf16_f32 v20, v72, v73
	v_cvt_pk_bf16_f32 v21, v74, v75
	global_store_dwordx4 v[58:59], v[18:21], off
	s_branch .LBB0_791

.Lw2_nowait:
	v_lshl_add_u32 v250, s52, 8, v146
	v_lshl_or_b32 v251, s26, 6, v148
	v_lshlrev_b32_e32 v251, 1, v251
	v_mbcnt_lo_u32_b32 v140, -1, 0
	v_mbcnt_hi_u32_b32 v140, -1, v140
	v_lshrrev_b32_e32 v141, 3, v140
	s_lshl_b32 s27, s3, 3
	v_add_u32_e32 v141, s27, v141
	v_and_b32_e32 v142, 7, v140
	v_bfe_u32 v143, v141, 1, 3
	v_xor_b32_e32 v142, v142, v143
	v_and_b32_e32 v143, 31, v141
	v_lshrrev_b32_e32 v141, 5, v141
	v_lshrrev_b32_e32 v144, 4, v143
	v_and_b32_e32 v143, 15, v143
	v_lshl_or_b32 v143, v144, 6, v143
	s_lshl_b32 s27, s52, 8
	v_add_u32_e32 v143, s27, v143
	v_lshlrev_b32_e32 v143, 13, v143
	v_lshl_add_u32 v143, v141, 11, v143
	v_lshl_add_u32 v143, v142, 4, v143
	s_lshl_b32 s27, s26, 7
	v_add_u32_e32 v143, s27, v143
	s_lshl_b32 s27, s3, 10
	s_add_i32 s27, s27, 0x20000
	v_add_u32_e32 v253, 0x0, v143
	s_add_i32 m0, s27, 0x0
	s_nop 0
	global_load_lds_dwordx4 v253, s[6:7]
	v_add_u32_e32 v253, 0x1000, v143
	s_add_i32 m0, s27, 0x2000
	s_nop 0
	global_load_lds_dwordx4 v253, s[6:7]
	v_lshrrev_b32_e32 v144, 6, v146
	v_and_b32_e32 v145, 15, v146
	v_lshl_or_b32 v144, v144, 4, v145
	v_bfe_u32 v145, v144, 1, 3
	v_lshrrev_b32_e32 v252, 4, v148
	v_bfe_u32 v254, v148, 3, 1
	v_lshl_or_b32 v252, v252, 1, v254
	v_xor_b32_e32 v252, v252, v145
	v_lshlrev_b32_e32 v252, 4, v252
	v_bfe_u32 v254, v148, 2, 1
	v_lshl_or_b32 v252, v254, 3, v252
	v_lshl_add_u32 v252, v144, 7, v252
	v_add_u32_e32 v252, 0x20000, v252
	v_mov_b32_e32 v224, 0xbfb8aa3b
	v_mov_b32_e32 v225, 0xbfb8aa3b
	v_mov_b32_e32 v226, 1.0
	v_mov_b32_e32 v227, 1.0
	v_mov_b32_e32 v228, 0
	v_mov_b32_e32 v229, 0
	v_pk_mul_f32 v[150:151], v[126:127], v[224:225]
	v_pk_mul_f32 v[152:153], v[128:129], v[224:225]
	v_pk_mul_f32 v[154:155], v[122:123], v[224:225]
	v_pk_mul_f32 v[156:157], v[124:125], v[224:225]
	v_pk_mul_f32 v[158:159], v[118:119], v[224:225]
	v_pk_mul_f32 v[160:161], v[120:121], v[224:225]
	v_pk_mul_f32 v[162:163], v[114:115], v[224:225]
	v_pk_mul_f32 v[164:165], v[116:117], v[224:225]
	v_exp_f32_e32 v150, v150
	v_exp_f32_e32 v151, v151
	v_exp_f32_e32 v152, v152
	v_exp_f32_e32 v153, v153
	v_exp_f32_e32 v154, v154
	v_exp_f32_e32 v155, v155
	v_exp_f32_e32 v156, v156
	v_exp_f32_e32 v157, v157
	v_exp_f32_e32 v158, v158
	v_exp_f32_e32 v159, v159
	v_exp_f32_e32 v160, v160
	v_exp_f32_e32 v161, v161
	v_exp_f32_e32 v162, v162
	v_exp_f32_e32 v163, v163
	v_exp_f32_e32 v164, v164
	v_exp_f32_e32 v165, v165
	v_pk_add_f32 v[150:151], v[150:151], v[226:227]
	v_pk_add_f32 v[152:153], v[152:153], v[226:227]
	v_pk_add_f32 v[154:155], v[154:155], v[226:227]
	v_pk_add_f32 v[156:157], v[156:157], v[226:227]
	v_pk_add_f32 v[158:159], v[158:159], v[226:227]
	v_pk_add_f32 v[160:161], v[160:161], v[226:227]
	v_pk_add_f32 v[162:163], v[162:163], v[226:227]
	v_pk_add_f32 v[164:165], v[164:165], v[226:227]
	v_rcp_f32_e32 v150, v150
	v_rcp_f32_e32 v151, v151
	v_rcp_f32_e32 v152, v152
	v_rcp_f32_e32 v153, v153
	v_rcp_f32_e32 v154, v154
	v_rcp_f32_e32 v155, v155
	v_rcp_f32_e32 v156, v156
	v_rcp_f32_e32 v157, v157
	v_rcp_f32_e32 v158, v158
	v_rcp_f32_e32 v159, v159
	v_rcp_f32_e32 v160, v160
	v_rcp_f32_e32 v161, v161
	v_rcp_f32_e32 v162, v162
	v_rcp_f32_e32 v163, v163
	v_rcp_f32_e32 v164, v164
	v_rcp_f32_e32 v165, v165
	v_pk_mul_f32 v[166:167], v[110:111], v[224:225]
	v_pk_mul_f32 v[168:169], v[112:113], v[224:225]
	v_pk_mul_f32 v[170:171], v[106:107], v[224:225]
	v_pk_mul_f32 v[172:173], v[108:109], v[224:225]
	v_pk_mul_f32 v[174:175], v[102:103], v[224:225]
	v_pk_mul_f32 v[176:177], v[104:105], v[224:225]
	v_pk_mul_f32 v[178:179], v[98:99], v[224:225]
	v_pk_mul_f32 v[180:181], v[100:101], v[224:225]
	v_exp_f32_e32 v166, v166
	v_exp_f32_e32 v167, v167
	v_exp_f32_e32 v168, v168
	v_exp_f32_e32 v169, v169
	v_exp_f32_e32 v170, v170
	v_exp_f32_e32 v171, v171
	v_exp_f32_e32 v172, v172
	v_exp_f32_e32 v173, v173
	v_exp_f32_e32 v174, v174
	v_exp_f32_e32 v175, v175
	v_exp_f32_e32 v176, v176
	v_exp_f32_e32 v177, v177
	v_exp_f32_e32 v178, v178
	v_exp_f32_e32 v179, v179
	v_exp_f32_e32 v180, v180
	v_exp_f32_e32 v181, v181
	v_pk_add_f32 v[166:167], v[166:167], v[226:227]
	v_pk_add_f32 v[168:169], v[168:169], v[226:227]
	v_pk_add_f32 v[170:171], v[170:171], v[226:227]
	v_pk_add_f32 v[172:173], v[172:173], v[226:227]
	v_pk_add_f32 v[174:175], v[174:175], v[226:227]
	v_pk_add_f32 v[176:177], v[176:177], v[226:227]
	v_pk_add_f32 v[178:179], v[178:179], v[226:227]
	v_pk_add_f32 v[180:181], v[180:181], v[226:227]
	v_rcp_f32_e32 v166, v166
	v_rcp_f32_e32 v167, v167
	v_rcp_f32_e32 v168, v168
	v_rcp_f32_e32 v169, v169
	v_rcp_f32_e32 v170, v170
	v_rcp_f32_e32 v171, v171
	v_rcp_f32_e32 v172, v172
	v_rcp_f32_e32 v173, v173
	v_rcp_f32_e32 v174, v174
	v_rcp_f32_e32 v175, v175
	v_rcp_f32_e32 v176, v176
	v_rcp_f32_e32 v177, v177
	v_rcp_f32_e32 v178, v178
	v_rcp_f32_e32 v179, v179
	v_rcp_f32_e32 v180, v180
	v_rcp_f32_e32 v181, v181
	v_pk_mul_f32 v[182:183], v[94:95], v[224:225]
	v_pk_mul_f32 v[184:185], v[96:97], v[224:225]
	v_pk_mul_f32 v[186:187], v[90:91], v[224:225]
	v_pk_mul_f32 v[188:189], v[92:93], v[224:225]
	v_pk_mul_f32 v[190:191], v[86:87], v[224:225]
	v_pk_mul_f32 v[192:193], v[88:89], v[224:225]
	v_pk_mul_f32 v[194:195], v[82:83], v[224:225]
	v_pk_mul_f32 v[196:197], v[84:85], v[224:225]
	v_exp_f32_e32 v182, v182
	v_exp_f32_e32 v183, v183
	v_exp_f32_e32 v184, v184
	v_exp_f32_e32 v185, v185
	v_exp_f32_e32 v186, v186
	v_exp_f32_e32 v187, v187
	v_exp_f32_e32 v188, v188
	v_exp_f32_e32 v189, v189
	v_exp_f32_e32 v190, v190
	v_exp_f32_e32 v191, v191
	v_exp_f32_e32 v192, v192
	v_exp_f32_e32 v193, v193
	v_exp_f32_e32 v194, v194
	v_exp_f32_e32 v195, v195
	v_exp_f32_e32 v196, v196
	v_exp_f32_e32 v197, v197
	v_pk_add_f32 v[182:183], v[182:183], v[226:227]
	v_pk_add_f32 v[184:185], v[184:185], v[226:227]
	v_pk_add_f32 v[186:187], v[186:187], v[226:227]
	v_pk_add_f32 v[188:189], v[188:189], v[226:227]
	v_pk_add_f32 v[190:191], v[190:191], v[226:227]
	v_pk_add_f32 v[192:193], v[192:193], v[226:227]
	v_pk_add_f32 v[194:195], v[194:195], v[226:227]
	v_pk_add_f32 v[196:197], v[196:197], v[226:227]
	v_rcp_f32_e32 v182, v182
	v_rcp_f32_e32 v183, v183
	v_rcp_f32_e32 v184, v184
	v_rcp_f32_e32 v185, v185
	v_rcp_f32_e32 v186, v186
	v_rcp_f32_e32 v187, v187
	v_rcp_f32_e32 v188, v188
	v_rcp_f32_e32 v189, v189
	v_rcp_f32_e32 v190, v190
	v_rcp_f32_e32 v191, v191
	v_rcp_f32_e32 v192, v192
	v_rcp_f32_e32 v193, v193
	v_rcp_f32_e32 v194, v194
	v_rcp_f32_e32 v195, v195
	v_rcp_f32_e32 v196, v196
	v_rcp_f32_e32 v197, v197
	s_waitcnt vmcnt(1)
	s_barrier
	v_add_u32_e32 v253, 0x20000, v143
	s_add_i32 m0, s27, 0x4000
	s_nop 0
	global_load_lds_dwordx4 v253, s[6:7]
	ds_read_b64 v[140:141], v252 offset:0
	ds_read_b64 v[144:145], v252 offset:4096
	v_pk_mul_f32 v[230:231], v[78:79], v[224:225]
	v_pk_mul_f32 v[232:233], v[80:81], v[224:225]
	v_pk_mul_f32 v[234:235], v[74:75], v[224:225]
	v_pk_mul_f32 v[236:237], v[76:77], v[224:225]
	v_exp_f32_e32 v230, v230
	v_exp_f32_e32 v231, v231
	v_exp_f32_e32 v232, v232
	v_exp_f32_e32 v233, v233
	v_exp_f32_e32 v234, v234
	v_exp_f32_e32 v235, v235
	v_exp_f32_e32 v236, v236
	v_exp_f32_e32 v237, v237
	v_pk_add_f32 v[230:231], v[230:231], v[226:227]
	v_pk_add_f32 v[232:233], v[232:233], v[226:227]
	v_pk_add_f32 v[234:235], v[234:235], v[226:227]
	v_pk_add_f32 v[236:237], v[236:237], v[226:227]
	v_rcp_f32_e32 v230, v230
	v_rcp_f32_e32 v231, v231
	v_rcp_f32_e32 v232, v232
	v_rcp_f32_e32 v233, v233
	v_rcp_f32_e32 v234, v234
	v_rcp_f32_e32 v235, v235
	v_rcp_f32_e32 v236, v236
	v_rcp_f32_e32 v237, v237
	s_waitcnt lgkmcnt(0)
	v_lshlrev_b32_e32 v126, 16, v140
	v_and_b32_e32 v127, 0xffff0000, v140
	v_lshlrev_b32_e32 v128, 16, v141
	v_and_b32_e32 v129, 0xffff0000, v141
	v_lshlrev_b32_e32 v122, 16, v144
	v_and_b32_e32 v123, 0xffff0000, v144
	v_lshlrev_b32_e32 v124, 16, v145
	v_and_b32_e32 v125, 0xffff0000, v145
	v_pk_mul_f32 v[150:151], v[150:151], v[126:127]
	v_pk_mul_f32 v[152:153], v[152:153], v[128:129]
	v_pk_mul_f32 v[154:155], v[154:155], v[122:123]
	v_pk_mul_f32 v[156:157], v[156:157], v[124:125]
	v_pk_add_f32 v[246:247], v[150:151], v[228:229]
	v_pk_add_f32 v[248:249], v[152:153], v[228:229]
	v_pk_add_f32 v[246:247], v[246:247], v[154:155]
	v_pk_add_f32 v[248:249], v[248:249], v[156:157]
	s_waitcnt vmcnt(1)
	s_barrier
	v_add_u32_e32 v253, 0x21000, v143
	s_add_i32 m0, s27, 0x0
	s_nop 0
	global_load_lds_dwordx4 v253, s[6:7]
	ds_read_b64 v[140:141], v252 offset:8192
	ds_read_b64 v[144:145], v252 offset:12288
	v_pk_mul_f32 v[238:239], v[70:71], v[224:225]
	v_pk_mul_f32 v[240:241], v[72:73], v[224:225]
	v_pk_mul_f32 v[242:243], v[66:67], v[224:225]
	v_pk_mul_f32 v[244:245], v[68:69], v[224:225]
	v_exp_f32_e32 v238, v238
	v_exp_f32_e32 v239, v239
	v_exp_f32_e32 v240, v240
	v_exp_f32_e32 v241, v241
	v_exp_f32_e32 v242, v242
	v_exp_f32_e32 v243, v243
	v_exp_f32_e32 v244, v244
	v_exp_f32_e32 v245, v245
	v_pk_add_f32 v[238:239], v[238:239], v[226:227]
	v_pk_add_f32 v[240:241], v[240:241], v[226:227]
	v_pk_add_f32 v[242:243], v[242:243], v[226:227]
	v_pk_add_f32 v[244:245], v[244:245], v[226:227]
	v_rcp_f32_e32 v238, v238
	v_rcp_f32_e32 v239, v239
	v_rcp_f32_e32 v240, v240
	v_rcp_f32_e32 v241, v241
	v_rcp_f32_e32 v242, v242
	v_rcp_f32_e32 v243, v243
	v_rcp_f32_e32 v244, v244
	v_rcp_f32_e32 v245, v245
	s_waitcnt lgkmcnt(0)
	v_lshlrev_b32_e32 v118, 16, v140
	v_and_b32_e32 v119, 0xffff0000, v140
	v_lshlrev_b32_e32 v120, 16, v141
	v_and_b32_e32 v121, 0xffff0000, v141
	v_lshlrev_b32_e32 v114, 16, v144
	v_and_b32_e32 v115, 0xffff0000, v144
	v_lshlrev_b32_e32 v116, 16, v145
	v_and_b32_e32 v117, 0xffff0000, v145
	v_pk_mul_f32 v[158:159], v[158:159], v[118:119]
	v_pk_mul_f32 v[160:161], v[160:161], v[120:121]
	v_pk_mul_f32 v[162:163], v[162:163], v[114:115]
	v_pk_mul_f32 v[164:165], v[164:165], v[116:117]
	v_pk_add_f32 v[246:247], v[246:247], v[158:159]
	v_pk_add_f32 v[248:249], v[248:249], v[160:161]
	v_pk_add_f32 v[246:247], v[246:247], v[162:163]
	v_pk_add_f32 v[248:249], v[248:249], v[164:165]
	v_add_u32_e32 v254, 0, v250
	v_cvt_pk_bf16_f32 v246, v246, v247
	v_cvt_pk_bf16_f32 v247, v248, v249
	v_lshl_add_u32 v254, v254, 11, v251
	s_nop 0
	global_store_dwordx2 v254, v[246:247], s[8:9]
	s_waitcnt vmcnt(2)
	s_barrier
	v_add_u32_e32 v253, 0x40000, v143
	s_add_i32 m0, s27, 0x2000
	s_nop 0
	global_load_lds_dwordx4 v253, s[6:7]
	ds_read_b64 v[140:141], v252 offset:16384
	ds_read_b64 v[144:145], v252 offset:20480
	v_pk_mul_f32 v[150:151], v[62:63], v[224:225]
	v_pk_mul_f32 v[152:153], v[64:65], v[224:225]
	v_pk_mul_f32 v[154:155], v[58:59], v[224:225]
	v_pk_mul_f32 v[156:157], v[60:61], v[224:225]
	v_exp_f32_e32 v150, v150
	v_exp_f32_e32 v151, v151
	v_exp_f32_e32 v152, v152
	v_exp_f32_e32 v153, v153
	v_exp_f32_e32 v154, v154
	v_exp_f32_e32 v155, v155
	v_exp_f32_e32 v156, v156
	v_exp_f32_e32 v157, v157
	v_pk_add_f32 v[150:151], v[150:151], v[226:227]
	v_pk_add_f32 v[152:153], v[152:153], v[226:227]
	v_pk_add_f32 v[154:155], v[154:155], v[226:227]
	v_pk_add_f32 v[156:157], v[156:157], v[226:227]
	v_rcp_f32_e32 v150, v150
	v_rcp_f32_e32 v151, v151
	v_rcp_f32_e32 v152, v152
	v_rcp_f32_e32 v153, v153
	v_rcp_f32_e32 v154, v154
	v_rcp_f32_e32 v155, v155
	v_rcp_f32_e32 v156, v156
	v_rcp_f32_e32 v157, v157
	s_waitcnt lgkmcnt(0)
	v_lshlrev_b32_e32 v110, 16, v140
	v_and_b32_e32 v111, 0xffff0000, v140
	v_lshlrev_b32_e32 v112, 16, v141
	v_and_b32_e32 v113, 0xffff0000, v141
	v_lshlrev_b32_e32 v106, 16, v144
	v_and_b32_e32 v107, 0xffff0000, v144
	v_lshlrev_b32_e32 v108, 16, v145
	v_and_b32_e32 v109, 0xffff0000, v145
	v_pk_mul_f32 v[166:167], v[166:167], v[110:111]
	v_pk_mul_f32 v[168:169], v[168:169], v[112:113]
	v_pk_mul_f32 v[170:171], v[170:171], v[106:107]
	v_pk_mul_f32 v[172:173], v[172:173], v[108:109]
	v_pk_add_f32 v[246:247], v[166:167], v[228:229]
	v_pk_add_f32 v[248:249], v[168:169], v[228:229]
	v_pk_add_f32 v[246:247], v[246:247], v[170:171]
	v_pk_add_f32 v[248:249], v[248:249], v[172:173]
	s_waitcnt vmcnt(2)
	s_barrier
	v_add_u32_e32 v253, 0x41000, v143
	s_add_i32 m0, s27, 0x4000
	s_nop 0
	global_load_lds_dwordx4 v253, s[6:7]
	ds_read_b64 v[140:141], v252 offset:0
	ds_read_b64 v[144:145], v252 offset:4096
	v_pk_mul_f32 v[158:159], v[54:55], v[224:225]
	v_pk_mul_f32 v[160:161], v[56:57], v[224:225]
	v_pk_mul_f32 v[162:163], v[50:51], v[224:225]
	v_pk_mul_f32 v[164:165], v[52:53], v[224:225]
	v_exp_f32_e32 v158, v158
	v_exp_f32_e32 v159, v159
	v_exp_f32_e32 v160, v160
	v_exp_f32_e32 v161, v161
	v_exp_f32_e32 v162, v162
	v_exp_f32_e32 v163, v163
	v_exp_f32_e32 v164, v164
	v_exp_f32_e32 v165, v165
	v_pk_add_f32 v[158:159], v[158:159], v[226:227]
	v_pk_add_f32 v[160:161], v[160:161], v[226:227]
	v_pk_add_f32 v[162:163], v[162:163], v[226:227]
	v_pk_add_f32 v[164:165], v[164:165], v[226:227]
	v_rcp_f32_e32 v158, v158
	v_rcp_f32_e32 v159, v159
	v_rcp_f32_e32 v160, v160
	v_rcp_f32_e32 v161, v161
	v_rcp_f32_e32 v162, v162
	v_rcp_f32_e32 v163, v163
	v_rcp_f32_e32 v164, v164
	v_rcp_f32_e32 v165, v165
	s_waitcnt lgkmcnt(0)
	v_lshlrev_b32_e32 v102, 16, v140
	v_and_b32_e32 v103, 0xffff0000, v140
	v_lshlrev_b32_e32 v104, 16, v141
	v_and_b32_e32 v105, 0xffff0000, v141
	v_lshlrev_b32_e32 v98, 16, v144
	v_and_b32_e32 v99, 0xffff0000, v144
	v_lshlrev_b32_e32 v100, 16, v145
	v_and_b32_e32 v101, 0xffff0000, v145
	v_pk_mul_f32 v[174:175], v[174:175], v[102:103]
	v_pk_mul_f32 v[176:177], v[176:177], v[104:105]
	v_pk_mul_f32 v[178:179], v[178:179], v[98:99]
	v_pk_mul_f32 v[180:181], v[180:181], v[100:101]
	v_pk_add_f32 v[246:247], v[246:247], v[174:175]
	v_pk_add_f32 v[248:249], v[248:249], v[176:177]
	v_pk_add_f32 v[246:247], v[246:247], v[178:179]
	v_pk_add_f32 v[248:249], v[248:249], v[180:181]
	v_add_u32_e32 v254, 16, v250
	v_cvt_pk_bf16_f32 v246, v246, v247
	v_cvt_pk_bf16_f32 v247, v248, v249
	v_lshl_add_u32 v254, v254, 11, v251
	s_nop 0
	global_store_dwordx2 v254, v[246:247], s[8:9]
	s_waitcnt vmcnt(2)
	s_barrier
	v_add_u32_e32 v253, 0x60000, v143
	s_add_i32 m0, s27, 0x0
	s_nop 0
	global_load_lds_dwordx4 v253, s[6:7]
	ds_read_b64 v[140:141], v252 offset:8192
	ds_read_b64 v[144:145], v252 offset:12288
	v_pk_mul_f32 v[166:167], v[46:47], v[224:225]
	v_pk_mul_f32 v[168:169], v[48:49], v[224:225]
	v_pk_mul_f32 v[170:171], v[42:43], v[224:225]
	v_pk_mul_f32 v[172:173], v[44:45], v[224:225]
	v_exp_f32_e32 v166, v166
	v_exp_f32_e32 v167, v167
	v_exp_f32_e32 v168, v168
	v_exp_f32_e32 v169, v169
	v_exp_f32_e32 v170, v170
	v_exp_f32_e32 v171, v171
	v_exp_f32_e32 v172, v172
	v_exp_f32_e32 v173, v173
	v_pk_add_f32 v[166:167], v[166:167], v[226:227]
	v_pk_add_f32 v[168:169], v[168:169], v[226:227]
	v_pk_add_f32 v[170:171], v[170:171], v[226:227]
	v_pk_add_f32 v[172:173], v[172:173], v[226:227]
	v_rcp_f32_e32 v166, v166
	v_rcp_f32_e32 v167, v167
	v_rcp_f32_e32 v168, v168
	v_rcp_f32_e32 v169, v169
	v_rcp_f32_e32 v170, v170
	v_rcp_f32_e32 v171, v171
	v_rcp_f32_e32 v172, v172
	v_rcp_f32_e32 v173, v173
	s_waitcnt lgkmcnt(0)
	v_lshlrev_b32_e32 v94, 16, v140
	v_and_b32_e32 v95, 0xffff0000, v140
	v_lshlrev_b32_e32 v96, 16, v141
	v_and_b32_e32 v97, 0xffff0000, v141
	v_lshlrev_b32_e32 v90, 16, v144
	v_and_b32_e32 v91, 0xffff0000, v144
	v_lshlrev_b32_e32 v92, 16, v145
	v_and_b32_e32 v93, 0xffff0000, v145
	v_pk_mul_f32 v[182:183], v[182:183], v[94:95]
	v_pk_mul_f32 v[184:185], v[184:185], v[96:97]
	v_pk_mul_f32 v[186:187], v[186:187], v[90:91]
	v_pk_mul_f32 v[188:189], v[188:189], v[92:93]
	v_pk_add_f32 v[246:247], v[182:183], v[228:229]
	v_pk_add_f32 v[248:249], v[184:185], v[228:229]
	v_pk_add_f32 v[246:247], v[246:247], v[186:187]
	v_pk_add_f32 v[248:249], v[248:249], v[188:189]
	s_waitcnt vmcnt(2)
	s_barrier
	v_add_u32_e32 v253, 0x61000, v143
	s_add_i32 m0, s27, 0x2000
	s_nop 0
	global_load_lds_dwordx4 v253, s[6:7]
	ds_read_b64 v[140:141], v252 offset:16384
	ds_read_b64 v[144:145], v252 offset:20480
	v_pk_mul_f32 v[174:175], v[38:39], v[224:225]
	v_pk_mul_f32 v[176:177], v[40:41], v[224:225]
	v_pk_mul_f32 v[178:179], v[34:35], v[224:225]
	v_pk_mul_f32 v[180:181], v[36:37], v[224:225]
	v_exp_f32_e32 v174, v174
	v_exp_f32_e32 v175, v175
	v_exp_f32_e32 v176, v176
	v_exp_f32_e32 v177, v177
	v_exp_f32_e32 v178, v178
	v_exp_f32_e32 v179, v179
	v_exp_f32_e32 v180, v180
	v_exp_f32_e32 v181, v181
	v_pk_add_f32 v[174:175], v[174:175], v[226:227]
	v_pk_add_f32 v[176:177], v[176:177], v[226:227]
	v_pk_add_f32 v[178:179], v[178:179], v[226:227]
	v_pk_add_f32 v[180:181], v[180:181], v[226:227]
	v_rcp_f32_e32 v174, v174
	v_rcp_f32_e32 v175, v175
	v_rcp_f32_e32 v176, v176
	v_rcp_f32_e32 v177, v177
	v_rcp_f32_e32 v178, v178
	v_rcp_f32_e32 v179, v179
	v_rcp_f32_e32 v180, v180
	v_rcp_f32_e32 v181, v181
	s_waitcnt lgkmcnt(0)
	v_lshlrev_b32_e32 v86, 16, v140
	v_and_b32_e32 v87, 0xffff0000, v140
	v_lshlrev_b32_e32 v88, 16, v141
	v_and_b32_e32 v89, 0xffff0000, v141
	v_lshlrev_b32_e32 v82, 16, v144
	v_and_b32_e32 v83, 0xffff0000, v144
	v_lshlrev_b32_e32 v84, 16, v145
	v_and_b32_e32 v85, 0xffff0000, v145
	v_pk_mul_f32 v[190:191], v[190:191], v[86:87]
	v_pk_mul_f32 v[192:193], v[192:193], v[88:89]
	v_pk_mul_f32 v[194:195], v[194:195], v[82:83]
	v_pk_mul_f32 v[196:197], v[196:197], v[84:85]
	v_pk_add_f32 v[246:247], v[246:247], v[190:191]
	v_pk_add_f32 v[248:249], v[248:249], v[192:193]
	v_pk_add_f32 v[246:247], v[246:247], v[194:195]
	v_pk_add_f32 v[248:249], v[248:249], v[196:197]
	v_add_u32_e32 v254, 32, v250
	v_cvt_pk_bf16_f32 v246, v246, v247
	v_cvt_pk_bf16_f32 v247, v248, v249
	v_lshl_add_u32 v254, v254, 11, v251
	s_nop 0
	global_store_dwordx2 v254, v[246:247], s[8:9]
	s_waitcnt vmcnt(2)
	s_barrier
	v_add_u32_e32 v253, 0x100000, v143
	s_add_i32 m0, s27, 0x4000
	s_nop 0
	global_load_lds_dwordx4 v253, s[6:7]
	ds_read_b64 v[140:141], v252 offset:0
	ds_read_b64 v[144:145], v252 offset:4096
	v_pk_mul_f32 v[182:183], v[30:31], v[224:225]
	v_pk_mul_f32 v[184:185], v[32:33], v[224:225]
	v_pk_mul_f32 v[186:187], v[26:27], v[224:225]
	v_pk_mul_f32 v[188:189], v[28:29], v[224:225]
	v_exp_f32_e32 v182, v182
	v_exp_f32_e32 v183, v183
	v_exp_f32_e32 v184, v184
	v_exp_f32_e32 v185, v185
	v_exp_f32_e32 v186, v186
	v_exp_f32_e32 v187, v187
	v_exp_f32_e32 v188, v188
	v_exp_f32_e32 v189, v189
	v_pk_add_f32 v[182:183], v[182:183], v[226:227]
	v_pk_add_f32 v[184:185], v[184:185], v[226:227]
	v_pk_add_f32 v[186:187], v[186:187], v[226:227]
	v_pk_add_f32 v[188:189], v[188:189], v[226:227]
	v_rcp_f32_e32 v182, v182
	v_rcp_f32_e32 v183, v183
	v_rcp_f32_e32 v184, v184
	v_rcp_f32_e32 v185, v185
	v_rcp_f32_e32 v186, v186
	v_rcp_f32_e32 v187, v187
	v_rcp_f32_e32 v188, v188
	v_rcp_f32_e32 v189, v189
	s_waitcnt lgkmcnt(0)
	v_lshlrev_b32_e32 v78, 16, v140
	v_and_b32_e32 v79, 0xffff0000, v140
	v_lshlrev_b32_e32 v80, 16, v141
	v_and_b32_e32 v81, 0xffff0000, v141
	v_lshlrev_b32_e32 v74, 16, v144
	v_and_b32_e32 v75, 0xffff0000, v144
	v_lshlrev_b32_e32 v76, 16, v145
	v_and_b32_e32 v77, 0xffff0000, v145
	v_pk_mul_f32 v[230:231], v[230:231], v[78:79]
	v_pk_mul_f32 v[232:233], v[232:233], v[80:81]
	v_pk_mul_f32 v[234:235], v[234:235], v[74:75]
	v_pk_mul_f32 v[236:237], v[236:237], v[76:77]
	v_pk_add_f32 v[246:247], v[230:231], v[228:229]
	v_pk_add_f32 v[248:249], v[232:233], v[228:229]
	v_pk_add_f32 v[246:247], v[246:247], v[234:235]
	v_pk_add_f32 v[248:249], v[248:249], v[236:237]
	s_waitcnt vmcnt(2)
	s_barrier
	v_add_u32_e32 v253, 0x101000, v143
	s_add_i32 m0, s27, 0x0
	s_nop 0
	global_load_lds_dwordx4 v253, s[6:7]
	ds_read_b64 v[140:141], v252 offset:8192
	ds_read_b64 v[144:145], v252 offset:12288
	v_pk_mul_f32 v[190:191], v[22:23], v[224:225]
	v_pk_mul_f32 v[192:193], v[24:25], v[224:225]
	v_pk_mul_f32 v[194:195], v[18:19], v[224:225]
	v_pk_mul_f32 v[196:197], v[20:21], v[224:225]
	v_exp_f32_e32 v190, v190
	v_exp_f32_e32 v191, v191
	v_exp_f32_e32 v192, v192
	v_exp_f32_e32 v193, v193
	v_exp_f32_e32 v194, v194
	v_exp_f32_e32 v195, v195
	v_exp_f32_e32 v196, v196
	v_exp_f32_e32 v197, v197
	v_pk_add_f32 v[190:191], v[190:191], v[226:227]
	v_pk_add_f32 v[192:193], v[192:193], v[226:227]
	v_pk_add_f32 v[194:195], v[194:195], v[226:227]
	v_pk_add_f32 v[196:197], v[196:197], v[226:227]
	v_rcp_f32_e32 v190, v190
	v_rcp_f32_e32 v191, v191
	v_rcp_f32_e32 v192, v192
	v_rcp_f32_e32 v193, v193
	v_rcp_f32_e32 v194, v194
	v_rcp_f32_e32 v195, v195
	v_rcp_f32_e32 v196, v196
	v_rcp_f32_e32 v197, v197
	s_waitcnt lgkmcnt(0)
	v_lshlrev_b32_e32 v70, 16, v140
	v_and_b32_e32 v71, 0xffff0000, v140
	v_lshlrev_b32_e32 v72, 16, v141
	v_and_b32_e32 v73, 0xffff0000, v141
	v_lshlrev_b32_e32 v66, 16, v144
	v_and_b32_e32 v67, 0xffff0000, v144
	v_lshlrev_b32_e32 v68, 16, v145
	v_and_b32_e32 v69, 0xffff0000, v145
	v_pk_mul_f32 v[238:239], v[238:239], v[70:71]
	v_pk_mul_f32 v[240:241], v[240:241], v[72:73]
	v_pk_mul_f32 v[242:243], v[242:243], v[66:67]
	v_pk_mul_f32 v[244:245], v[244:245], v[68:69]
	v_pk_add_f32 v[246:247], v[246:247], v[238:239]
	v_pk_add_f32 v[248:249], v[248:249], v[240:241]
	v_pk_add_f32 v[246:247], v[246:247], v[242:243]
	v_pk_add_f32 v[248:249], v[248:249], v[244:245]
	v_add_u32_e32 v254, 48, v250
	v_cvt_pk_bf16_f32 v246, v246, v247
	v_cvt_pk_bf16_f32 v247, v248, v249
	v_lshl_add_u32 v254, v254, 11, v251
	s_nop 0
	global_store_dwordx2 v254, v[246:247], s[8:9]
	s_waitcnt vmcnt(2)
	s_barrier
	v_add_u32_e32 v253, 0x120000, v143
	s_add_i32 m0, s27, 0x2000
	s_nop 0
	global_load_lds_dwordx4 v253, s[6:7]
	ds_read_b64 v[140:141], v252 offset:16384
	ds_read_b64 v[144:145], v252 offset:20480
	v_pk_mul_f32 v[230:231], v[14:15], v[224:225]
	v_pk_mul_f32 v[232:233], v[16:17], v[224:225]
	v_pk_mul_f32 v[234:235], v[10:11], v[224:225]
	v_pk_mul_f32 v[236:237], v[12:13], v[224:225]
	v_exp_f32_e32 v230, v230
	v_exp_f32_e32 v231, v231
	v_exp_f32_e32 v232, v232
	v_exp_f32_e32 v233, v233
	v_exp_f32_e32 v234, v234
	v_exp_f32_e32 v235, v235
	v_exp_f32_e32 v236, v236
	v_exp_f32_e32 v237, v237
	v_pk_add_f32 v[230:231], v[230:231], v[226:227]
	v_pk_add_f32 v[232:233], v[232:233], v[226:227]
	v_pk_add_f32 v[234:235], v[234:235], v[226:227]
	v_pk_add_f32 v[236:237], v[236:237], v[226:227]
	v_rcp_f32_e32 v230, v230
	v_rcp_f32_e32 v231, v231
	v_rcp_f32_e32 v232, v232
	v_rcp_f32_e32 v233, v233
	v_rcp_f32_e32 v234, v234
	v_rcp_f32_e32 v235, v235
	v_rcp_f32_e32 v236, v236
	v_rcp_f32_e32 v237, v237
	s_waitcnt lgkmcnt(0)
	v_lshlrev_b32_e32 v62, 16, v140
	v_and_b32_e32 v63, 0xffff0000, v140
	v_lshlrev_b32_e32 v64, 16, v141
	v_and_b32_e32 v65, 0xffff0000, v141
	v_lshlrev_b32_e32 v58, 16, v144
	v_and_b32_e32 v59, 0xffff0000, v144
	v_lshlrev_b32_e32 v60, 16, v145
	v_and_b32_e32 v61, 0xffff0000, v145
	v_pk_mul_f32 v[150:151], v[150:151], v[62:63]
	v_pk_mul_f32 v[152:153], v[152:153], v[64:65]
	v_pk_mul_f32 v[154:155], v[154:155], v[58:59]
	v_pk_mul_f32 v[156:157], v[156:157], v[60:61]
	v_pk_add_f32 v[246:247], v[150:151], v[228:229]
	v_pk_add_f32 v[248:249], v[152:153], v[228:229]
	v_pk_add_f32 v[246:247], v[246:247], v[154:155]
	v_pk_add_f32 v[248:249], v[248:249], v[156:157]
	s_waitcnt vmcnt(2)
	s_barrier
	v_add_u32_e32 v253, 0x121000, v143
	s_add_i32 m0, s27, 0x4000
	s_nop 0
	global_load_lds_dwordx4 v253, s[6:7]
	ds_read_b64 v[140:141], v252 offset:0
	ds_read_b64 v[144:145], v252 offset:4096
	v_pk_mul_f32 v[238:239], v[6:7], v[224:225]
	v_pk_mul_f32 v[240:241], v[8:9], v[224:225]
	v_pk_mul_f32 v[242:243], v[2:3], v[224:225]
	v_pk_mul_f32 v[244:245], v[4:5], v[224:225]
	v_exp_f32_e32 v238, v238
	v_exp_f32_e32 v239, v239
	v_exp_f32_e32 v240, v240
	v_exp_f32_e32 v241, v241
	v_exp_f32_e32 v242, v242
	v_exp_f32_e32 v243, v243
	v_exp_f32_e32 v244, v244
	v_exp_f32_e32 v245, v245
	v_pk_add_f32 v[238:239], v[238:239], v[226:227]
	v_pk_add_f32 v[240:241], v[240:241], v[226:227]
	v_pk_add_f32 v[242:243], v[242:243], v[226:227]
	v_pk_add_f32 v[244:245], v[244:245], v[226:227]
	v_rcp_f32_e32 v238, v238
	v_rcp_f32_e32 v239, v239
	v_rcp_f32_e32 v240, v240
	v_rcp_f32_e32 v241, v241
	v_rcp_f32_e32 v242, v242
	v_rcp_f32_e32 v243, v243
	v_rcp_f32_e32 v244, v244
	v_rcp_f32_e32 v245, v245
	s_waitcnt lgkmcnt(0)
	v_lshlrev_b32_e32 v54, 16, v140
	v_and_b32_e32 v55, 0xffff0000, v140
	v_lshlrev_b32_e32 v56, 16, v141
	v_and_b32_e32 v57, 0xffff0000, v141
	v_lshlrev_b32_e32 v50, 16, v144
	v_and_b32_e32 v51, 0xffff0000, v144
	v_lshlrev_b32_e32 v52, 16, v145
	v_and_b32_e32 v53, 0xffff0000, v145
	v_pk_mul_f32 v[158:159], v[158:159], v[54:55]
	v_pk_mul_f32 v[160:161], v[160:161], v[56:57]
	v_pk_mul_f32 v[162:163], v[162:163], v[50:51]
	v_pk_mul_f32 v[164:165], v[164:165], v[52:53]
	v_pk_add_f32 v[246:247], v[246:247], v[158:159]
	v_pk_add_f32 v[248:249], v[248:249], v[160:161]
	v_pk_add_f32 v[246:247], v[246:247], v[162:163]
	v_pk_add_f32 v[248:249], v[248:249], v[164:165]
	v_add_u32_e32 v254, 128, v250
	v_cvt_pk_bf16_f32 v246, v246, v247
	v_cvt_pk_bf16_f32 v247, v248, v249
	v_lshl_add_u32 v254, v254, 11, v251
	s_nop 0
	global_store_dwordx2 v254, v[246:247], s[8:9]
	s_waitcnt vmcnt(2)
	s_barrier
	v_add_u32_e32 v253, 0x140000, v143
	s_add_i32 m0, s27, 0x0
	s_nop 0
	global_load_lds_dwordx4 v253, s[6:7]
	ds_read_b64 v[140:141], v252 offset:8192
	ds_read_b64 v[144:145], v252 offset:12288
	s_waitcnt lgkmcnt(0)
	v_lshlrev_b32_e32 v46, 16, v140
	v_and_b32_e32 v47, 0xffff0000, v140
	v_lshlrev_b32_e32 v48, 16, v141
	v_and_b32_e32 v49, 0xffff0000, v141
	v_lshlrev_b32_e32 v42, 16, v144
	v_and_b32_e32 v43, 0xffff0000, v144
	v_lshlrev_b32_e32 v44, 16, v145
	v_and_b32_e32 v45, 0xffff0000, v145
	v_pk_mul_f32 v[166:167], v[166:167], v[46:47]
	v_pk_mul_f32 v[168:169], v[168:169], v[48:49]
	v_pk_mul_f32 v[170:171], v[170:171], v[42:43]
	v_pk_mul_f32 v[172:173], v[172:173], v[44:45]
	v_pk_add_f32 v[246:247], v[166:167], v[228:229]
	v_pk_add_f32 v[248:249], v[168:169], v[228:229]
	v_pk_add_f32 v[246:247], v[246:247], v[170:171]
	v_pk_add_f32 v[248:249], v[248:249], v[172:173]
	s_waitcnt vmcnt(2)
	s_barrier
	v_add_u32_e32 v253, 0x141000, v143
	s_add_i32 m0, s27, 0x2000
	s_nop 0
	global_load_lds_dwordx4 v253, s[6:7]
	ds_read_b64 v[140:141], v252 offset:16384
	ds_read_b64 v[144:145], v252 offset:20480
	s_waitcnt lgkmcnt(0)
	v_lshlrev_b32_e32 v38, 16, v140
	v_and_b32_e32 v39, 0xffff0000, v140
	v_lshlrev_b32_e32 v40, 16, v141
	v_and_b32_e32 v41, 0xffff0000, v141
	v_lshlrev_b32_e32 v34, 16, v144
	v_and_b32_e32 v35, 0xffff0000, v144
	v_lshlrev_b32_e32 v36, 16, v145
	v_and_b32_e32 v37, 0xffff0000, v145
	v_pk_mul_f32 v[174:175], v[174:175], v[38:39]
	v_pk_mul_f32 v[176:177], v[176:177], v[40:41]
	v_pk_mul_f32 v[178:179], v[178:179], v[34:35]
	v_pk_mul_f32 v[180:181], v[180:181], v[36:37]
	v_pk_add_f32 v[246:247], v[246:247], v[174:175]
	v_pk_add_f32 v[248:249], v[248:249], v[176:177]
	v_pk_add_f32 v[246:247], v[246:247], v[178:179]
	v_pk_add_f32 v[248:249], v[248:249], v[180:181]
	v_add_u32_e32 v254, 144, v250
	v_cvt_pk_bf16_f32 v246, v246, v247
	v_cvt_pk_bf16_f32 v247, v248, v249
	v_lshl_add_u32 v254, v254, 11, v251
	s_nop 0
	global_store_dwordx2 v254, v[246:247], s[8:9]
	s_waitcnt vmcnt(2)
	s_barrier
	v_add_u32_e32 v253, 0x160000, v143
	s_add_i32 m0, s27, 0x4000
	s_nop 0
	global_load_lds_dwordx4 v253, s[6:7]
	ds_read_b64 v[140:141], v252 offset:0
	ds_read_b64 v[144:145], v252 offset:4096
	s_waitcnt lgkmcnt(0)
	v_lshlrev_b32_e32 v30, 16, v140
	v_and_b32_e32 v31, 0xffff0000, v140
	v_lshlrev_b32_e32 v32, 16, v141
	v_and_b32_e32 v33, 0xffff0000, v141
	v_lshlrev_b32_e32 v26, 16, v144
	v_and_b32_e32 v27, 0xffff0000, v144
	v_lshlrev_b32_e32 v28, 16, v145
	v_and_b32_e32 v29, 0xffff0000, v145
	v_pk_mul_f32 v[182:183], v[182:183], v[30:31]
	v_pk_mul_f32 v[184:185], v[184:185], v[32:33]
	v_pk_mul_f32 v[186:187], v[186:187], v[26:27]
	v_pk_mul_f32 v[188:189], v[188:189], v[28:29]
	v_pk_add_f32 v[246:247], v[182:183], v[228:229]
	v_pk_add_f32 v[248:249], v[184:185], v[228:229]
	v_pk_add_f32 v[246:247], v[246:247], v[186:187]
	v_pk_add_f32 v[248:249], v[248:249], v[188:189]
	s_waitcnt vmcnt(2)
	s_barrier
	v_add_u32_e32 v253, 0x161000, v143
	s_add_i32 m0, s27, 0x0
	s_nop 0
	global_load_lds_dwordx4 v253, s[6:7]
	ds_read_b64 v[140:141], v252 offset:8192
	ds_read_b64 v[144:145], v252 offset:12288
	s_waitcnt lgkmcnt(0)
	v_lshlrev_b32_e32 v22, 16, v140
	v_and_b32_e32 v23, 0xffff0000, v140
	v_lshlrev_b32_e32 v24, 16, v141
	v_and_b32_e32 v25, 0xffff0000, v141
	v_lshlrev_b32_e32 v18, 16, v144
	v_and_b32_e32 v19, 0xffff0000, v144
	v_lshlrev_b32_e32 v20, 16, v145
	v_and_b32_e32 v21, 0xffff0000, v145
	v_pk_mul_f32 v[190:191], v[190:191], v[22:23]
	v_pk_mul_f32 v[192:193], v[192:193], v[24:25]
	v_pk_mul_f32 v[194:195], v[194:195], v[18:19]
	v_pk_mul_f32 v[196:197], v[196:197], v[20:21]
	v_pk_add_f32 v[246:247], v[246:247], v[190:191]
	v_pk_add_f32 v[248:249], v[248:249], v[192:193]
	v_pk_add_f32 v[246:247], v[246:247], v[194:195]
	v_pk_add_f32 v[248:249], v[248:249], v[196:197]
	v_add_u32_e32 v254, 160, v250
	v_cvt_pk_bf16_f32 v246, v246, v247
	v_cvt_pk_bf16_f32 v247, v248, v249
	v_lshl_add_u32 v254, v254, 11, v251
	s_nop 0
	global_store_dwordx2 v254, v[246:247], s[8:9]
	s_waitcnt vmcnt(2)
	s_barrier
	ds_read_b64 v[140:141], v252 offset:16384
	ds_read_b64 v[144:145], v252 offset:20480
	s_waitcnt lgkmcnt(0)
	v_lshlrev_b32_e32 v14, 16, v140
	v_and_b32_e32 v15, 0xffff0000, v140
	v_lshlrev_b32_e32 v16, 16, v141
	v_and_b32_e32 v17, 0xffff0000, v141
	v_lshlrev_b32_e32 v10, 16, v144
	v_and_b32_e32 v11, 0xffff0000, v144
	v_lshlrev_b32_e32 v12, 16, v145
	v_and_b32_e32 v13, 0xffff0000, v145
	v_pk_mul_f32 v[230:231], v[230:231], v[14:15]
	v_pk_mul_f32 v[232:233], v[232:233], v[16:17]
	v_pk_mul_f32 v[234:235], v[234:235], v[10:11]
	v_pk_mul_f32 v[236:237], v[236:237], v[12:13]
	v_pk_add_f32 v[246:247], v[230:231], v[228:229]
	v_pk_add_f32 v[248:249], v[232:233], v[228:229]
	v_pk_add_f32 v[246:247], v[246:247], v[234:235]
	v_pk_add_f32 v[248:249], v[248:249], v[236:237]
	s_waitcnt vmcnt(1)
	s_barrier
	ds_read_b64 v[140:141], v252 offset:0
	ds_read_b64 v[144:145], v252 offset:4096
	s_waitcnt lgkmcnt(0)
	v_lshlrev_b32_e32 v6, 16, v140
	v_and_b32_e32 v7, 0xffff0000, v140
	v_lshlrev_b32_e32 v8, 16, v141
	v_and_b32_e32 v9, 0xffff0000, v141
	v_lshlrev_b32_e32 v2, 16, v144
	v_and_b32_e32 v3, 0xffff0000, v144
	v_lshlrev_b32_e32 v4, 16, v145
	v_and_b32_e32 v5, 0xffff0000, v145
	v_pk_mul_f32 v[238:239], v[238:239], v[6:7]
	v_pk_mul_f32 v[240:241], v[240:241], v[8:9]
	v_pk_mul_f32 v[242:243], v[242:243], v[2:3]
	v_pk_mul_f32 v[244:245], v[244:245], v[4:5]
	v_pk_add_f32 v[246:247], v[246:247], v[238:239]
	v_pk_add_f32 v[248:249], v[248:249], v[240:241]
	v_pk_add_f32 v[246:247], v[246:247], v[242:243]
	v_pk_add_f32 v[248:249], v[248:249], v[244:245]
	v_add_u32_e32 v254, 176, v250
	v_cvt_pk_bf16_f32 v246, v246, v247
	v_cvt_pk_bf16_f32 v247, v248, v249
	v_lshl_add_u32 v254, v254, 11, v251
	s_nop 0
	global_store_dwordx2 v254, v[246:247], s[8:9]
	s_mov_b64 s[26:27], -1
	s_andn2_b64 vcc, exec, s[4:5]
	s_cbranch_vccnz .LBB0_1599
	s_andn2_b64 vcc, exec, s[0:1]
	s_cbranch_vccnz .LBB0_1598
	s_barrier
	s_branch .LBB0_1598
